# nt hint on LN1 bf16 x1 stores (re-read only three phases later)
# baseline (speedup 1.0000x reference)
; #define LAS __attribute__((address_space(3)))
; __device__ __forceinline__ unsigned pk2(float lo, float hi) { unsigned r; asm("v_cvt_pk_bf16_f32 %0, %1, %2" : "=v"(r) : "v"(lo), "v"(hi)); return r; }
; __device__ __forceinline__ unsigned pk4_fp8(float a, float b, float c, float d) { int w = 0; w = __builtin_amdgcn_cvt_pk_fp8_f32(a, b, w, false); w = __builtin_amdgcn_cvt_pk_fp8_f32(c, d, w, true); return (unsigned)w; }
; __device__ __forceinline__ float bflo(unsigned u) { return __uint_as_float(u << 16); }
; __device__ __forceinline__ float bfhi(unsigned u) { return __uint_as_float(u & 0xffff0000u); }
; __device__ __forceinline__ void ln1_router_phase(const Args& a, int l, LAS unsigned char* lds, const int tid, const int rpt) {
;     ...
;         for (int rr = 0; rr < 2; ++rr) { const int lr = 2 * wave + rr;
;             f32x4 v[4]; float s = 0.f;
; #pragma unroll
;             for (int j = 0; j < 4; ++j) { const u32x2 w = pre[rr][j]; v[j] = (f32x4){bflo(w.x), bfhi(w.x), bflo(w.y), bfhi(w.y)}; s += (v[j][0] + v[j][1]) + (v[j][2] + v[j][3]); }
;             const float mean = wave_sum(s, lane) * (1.f / 1024.f); float s2 = 0.f;
; #pragma unroll
;             for (int j = 0; j < 4; ++j) { v[j] = v[j] - mean; s2 += (v[j][0] * v[j][0] + v[j][1] * v[j][1]) + (v[j][2] * v[j][2] + v[j][3] * v[j][3]); }
;             const float rstd = rsqrtf(wave_sum(s2, lane) * (1.f / 1024.f) + LN_EPS);
; #pragma unroll
;             for (int j = 0; j < 4; ++j) { const f32x4 y = v[j] * rstd * gv[j] + bv[j];
;                 u32x2 w; w.x = pk2(y[0], y[1]); w.y = pk2(y[2], y[3]); *(u32x2*)(x1b + (size_t)(tok0 + lr) * 1024 + 4 * (64 * j + lane)) = w;
;                 *(unsigned*)(x1q + (size_t)(tok0 + lr) * 1024 + 4 * (64 * j + lane)) = pk4_fp8(y[0], y[1], y[2], y[3]);
;                 *(LAS f32x4*)(X + lr * 1028 + 4 * (64 * j + lane)) = y; } }
.LBB0_123:
	s_waitcnt vmcnt(7)
	v_lshlrev_b32_e32 v153, 16, v35
	v_lshlrev_b32_e32 v152, 16, v34
	v_and_b32_e32 v155, 0xffff0000, v35
	v_and_b32_e32 v154, 0xffff0000, v34
	s_waitcnt vmcnt(6)
	v_lshlrev_b32_e32 v157, 16, v37
	v_lshlrev_b32_e32 v156, 16, v36
	v_and_b32_e32 v159, 0xffff0000, v37
	v_and_b32_e32 v158, 0xffff0000, v36
	v_pk_add_f32 v[64:65], v[152:153], v[154:155]
	v_pk_add_f32 v[66:67], v[156:157], v[158:159]
	v_add_f32_e32 v32, v64, v65
	v_pk_add_f32 v[66:67], v[66:67], v[66:67] op_sel_hi:[0,1]
	s_waitcnt vmcnt(5)
	v_lshlrev_b32_e32 v72, 16, v40
	v_and_b32_e32 v73, 0xffff0000, v40
	v_lshlrev_b32_e32 v74, 16, v41
	v_and_b32_e32 v75, 0xffff0000, v41
	v_add_f32_e32 v65, 0, v32
	v_add_f32_e32 v69, v72, v73
	v_add_f32_e32 v71, v74, v75
	s_waitcnt vmcnt(4)
	v_lshlrev_b32_e32 v68, 16, v42
	v_and_b32_e32 v70, 0xffff0000, v42
	v_lshlrev_b32_e32 v66, 16, v43
	v_and_b32_e32 v64, 0xffff0000, v43
	v_pk_add_f32 v[160:161], v[68:69], v[70:71]
	v_pk_add_f32 v[162:163], v[66:67], v[64:65]
	v_mov_b32_e32 v45, v33
	v_pk_add_f32 v[160:161], v[160:161], v[162:163]
	s_lshl_b32 s51, s50, 4
	v_add_f32_e32 v32, v160, v161
	s_nop 1
	v_add_f32_dpp v32, v32, v32 quad_perm:[1,0,3,2] row_mask:0xf bank_mask:0xf bound_ctrl:1
	s_nop 1
	v_add_f32_dpp v32, v32, v32 quad_perm:[2,3,0,1] row_mask:0xf bank_mask:0xf bound_ctrl:1
	s_nop 1
	v_add_f32_dpp v32, v32, v32 row_half_mirror row_mask:0xf bank_mask:0xf bound_ctrl:1
	s_nop 1
	v_add_f32_dpp v32, v32, v32 row_mirror row_mask:0xf bank_mask:0xf bound_ctrl:1
	s_nop 1
	v_mov_b32_dpp v45, v32 row_bcast:15 row_mask:0xa bank_mask:0xf
	v_add_f32_e32 v32, v32, v45
	v_mov_b32_e32 v45, v33
	s_nop 1
	v_mov_b32_dpp v45, v32 row_bcast:31 row_mask:0xc bank_mask:0xf
	v_add_f32_e32 v32, v32, v45
	v_mov_b32_e32 v45, v33
	v_readlane_b32 s0, v32, 63
	s_nop 1
	v_fmac_f32_e32 v154, s0, v210
	v_fmac_f32_e32 v155, s0, v210
	v_fmac_f32_e32 v153, s0, v210
	v_fmac_f32_e32 v152, s0, v210
	v_mov_b32_e32 v160, v153
	v_mov_b32_e32 v161, v155
	v_mov_b32_e32 v153, v154
	v_pk_mul_f32 v[162:163], v[160:161], v[160:161]
	v_pk_mul_f32 v[154:155], v[152:153], v[152:153]
	v_fmac_f32_e32 v158, s0, v210
	v_fmac_f32_e32 v159, s0, v210
	v_fmac_f32_e32 v157, s0, v210
	v_pk_mov_b32 v[172:173], v[154:155], v[162:163] op_sel:[1,0]
	v_mov_b32_e32 v155, v163
	v_fmac_f32_e32 v156, s0, v210
	v_mov_b32_e32 v162, v157
	v_mov_b32_e32 v163, v159
	v_mov_b32_e32 v157, v158
	v_pk_add_f32 v[154:155], v[172:173], v[154:155]
	v_pk_mul_f32 v[172:173], v[162:163], v[162:163]
	v_pk_mul_f32 v[158:159], v[156:157], v[156:157]
	v_fmac_f32_e32 v72, s0, v210
	v_pk_mov_b32 v[174:175], v[158:159], v[172:173] op_sel:[1,0]
	v_mov_b32_e32 v159, v173
	v_fmac_f32_e32 v73, s0, v210
	v_fmac_f32_e32 v74, s0, v210
	v_mul_f32_e32 v32, v72, v72
	v_pk_add_f32 v[158:159], v[174:175], v[158:159]
	v_fmac_f32_e32 v75, s0, v210
	v_pk_fma_f32 v[172:173], v[72:73], v[72:73], v[32:33] op_sel_hi:[1,1,0]
	v_mul_f32_e32 v32, v74, v74
	v_pk_add_f32 v[154:155], v[154:155], v[154:155] op_sel_hi:[0,1]
	v_pk_add_f32 v[158:159], v[158:159], v[158:159] op_sel_hi:[0,1]
	v_pk_fma_f32 v[174:175], v[74:75], v[74:75], v[32:33] op_sel_hi:[1,1,0]
	v_fmac_f32_e32 v64, s0, v210
	v_fmac_f32_e32 v66, s0, v210
	v_fmac_f32_e32 v70, s0, v210
	v_fmac_f32_e32 v68, s0, v210
	v_mul_f32_e32 v172, v68, v68
	v_mul_f32_e32 v174, v70, v70
	v_mul_f32_e32 v154, v66, v66
	v_mul_f32_e32 v158, v64, v64
	v_pk_add_f32 v[172:173], v[172:173], v[174:175]
	v_pk_add_f32 v[154:155], v[154:155], v[158:159]
	v_mov_b32_e32 v69, v70
	v_pk_add_f32 v[154:155], v[172:173], v[154:155]
	v_mov_b32_e32 v67, v64
	v_add_f32_e32 v32, v154, v155
	s_waitcnt vmcnt(0)
	v_and_b32_e32 v70, 0xffff0000, v54
	v_add_f32_dpp v32, v32, v32 quad_perm:[1,0,3,2] row_mask:0xf bank_mask:0xf bound_ctrl:1
	s_nop 1
	v_add_f32_dpp v32, v32, v32 quad_perm:[2,3,0,1] row_mask:0xf bank_mask:0xf bound_ctrl:1
	s_nop 1
	v_add_f32_dpp v32, v32, v32 row_half_mirror row_mask:0xf bank_mask:0xf bound_ctrl:1
	s_nop 1
	v_add_f32_dpp v32, v32, v32 row_mirror row_mask:0xf bank_mask:0xf bound_ctrl:1
	s_nop 1
	v_mov_b32_dpp v45, v32 row_bcast:15 row_mask:0xa bank_mask:0xf
	v_add_f32_e32 v32, v32, v45
	v_mov_b32_e32 v45, v33
	s_nop 1
	v_mov_b32_dpp v45, v32 row_bcast:31 row_mask:0xc bank_mask:0xf
	v_add_f32_e32 v32, v32, v45
	s_nop 0
	v_readlane_b32 s0, v32, 63
	s_nop 1
	v_fma_f32 v32, s0, v247, v206
	v_cmp_gt_f32_e32 vcc, s33, v32
	v_mul_f32_e32 v45, 0x4b800000, v32
	s_add_i32 s0, s51, s15
	v_cndmask_b32_e32 v32, v32, v45, vcc
	v_rsq_f32_e32 v32, v32
	s_ashr_i32 s1, s0, 31
	s_lshl_b64 s[20:21], s[0:1], 10
	s_lshl_b64 s[0:1], s[0:1], 11
	v_mul_f32_e32 v45, 0x45800000, v32
	v_cndmask_b32_e32 v32, v32, v45, vcc
	v_pk_mul_f32 v[152:153], v[152:153], v[32:33] op_sel_hi:[1,0]
	v_mov_b32_e32 v45, v33
	v_pk_fma_f32 v[152:153], v[0:1], v[152:153], v[8:9]
	v_pk_mul_f32 v[154:155], v[160:161], v[32:33] op_sel_hi:[1,0]
	v_cvt_pk_fp8_f32 v45, v152, v153
	v_pk_fma_f32 v[154:155], v[2:3], v[154:155], v[10:11]
	v_cvt_pk_bf16_f32 v158, v152, v153
	v_lshl_add_u64 v[160:161], v[58:59], 0, s[0:1]
	v_cvt_pk_fp8_f32 v45, v154, v155 op_sel:[0,0,1]
	v_cvt_pk_bf16_f32 v159, v154, v155
	global_store_dwordx2 v[160:161], v[158:159], off nt
	v_lshl_add_u64 v[158:159], v[60:61], 0, s[20:21]
	ds_write_b128 v148, v[152:155]
	v_pk_mul_f32 v[152:153], v[156:157], v[32:33] op_sel_hi:[1,0]
	global_store_dword v[158:159], v45, off
	v_pk_fma_f32 v[152:153], v[4:5], v[152:153], v[12:13]
	v_mov_b32_e32 v45, v33
	v_cvt_pk_fp8_f32 v45, v152, v153
	v_pk_mul_f32 v[154:155], v[162:163], v[32:33] op_sel_hi:[1,0]
	v_pk_mul_f32 v[72:73], v[72:73], v[32:33] op_sel_hi:[1,0]
	v_pk_fma_f32 v[154:155], v[6:7], v[154:155], v[14:15]
; #define LAS __attribute__((address_space(3)))
; __device__ __forceinline__ unsigned pk2(float lo, float hi) { unsigned r; asm("v_cvt_pk_bf16_f32 %0, %1, %2" : "=v"(r) : "v"(lo), "v"(hi)); return r; }
; __device__ __forceinline__ unsigned pk4_fp8(float a, float b, float c, float d) { int w = 0; w = __builtin_amdgcn_cvt_pk_fp8_f32(a, b, w, false); w = __builtin_amdgcn_cvt_pk_fp8_f32(c, d, w, true); return (unsigned)w; }
; __device__ __forceinline__ float bflo(unsigned u) { return __uint_as_float(u << 16); }
; __device__ __forceinline__ float bfhi(unsigned u) { return __uint_as_float(u & 0xffff0000u); }
; __device__ __forceinline__ void ln1_router_phase(const Args& a, int l, LAS unsigned char* lds, const int tid, const int rpt) {
;     ...
;         for (int rr = 0; rr < 2; ++rr) { const int lr = 2 * wave + rr;
;             f32x4 v[4]; float s = 0.f;
; #pragma unroll
;             for (int j = 0; j < 4; ++j) { const u32x2 w = pre[rr][j]; v[j] = (f32x4){bflo(w.x), bfhi(w.x), bflo(w.y), bfhi(w.y)}; s += (v[j][0] + v[j][1]) + (v[j][2] + v[j][3]); }
;             const float mean = wave_sum(s, lane) * (1.f / 1024.f); float s2 = 0.f;
; #pragma unroll
;             for (int j = 0; j < 4; ++j) { v[j] = v[j] - mean; s2 += (v[j][0] * v[j][0] + v[j][1] * v[j][1]) + (v[j][2] * v[j][2] + v[j][3] * v[j][3]); }
;             const float rstd = rsqrtf(wave_sum(s2, lane) * (1.f / 1024.f) + LN_EPS);
; #pragma unroll
;             for (int j = 0; j < 4; ++j) { const f32x4 y = v[j] * rstd * gv[j] + bv[j];
;                 u32x2 w; w.x = pk2(y[0], y[1]); w.y = pk2(y[2], y[3]); *(u32x2*)(x1b + (size_t)(tok0 + lr) * 1024 + 4 * (64 * j + lane)) = w;
;                 *(unsigned*)(x1q + (size_t)(tok0 + lr) * 1024 + 4 * (64 * j + lane)) = pk4_fp8(y[0], y[1], y[2], y[3]);
;                 *(LAS f32x4*)(X + lr * 1028 + 4 * (64 * j + lane)) = y; } }
	v_pk_mul_f32 v[68:69], v[68:69], v[32:33] op_sel_hi:[1,0]
	v_cvt_pk_fp8_f32 v45, v154, v155 op_sel:[0,0,1]
	v_pk_mul_f32 v[64:65], v[66:67], v[32:33] op_sel_hi:[1,0]
	v_cvt_pk_bf16_f32 v156, v152, v153
	v_cvt_pk_bf16_f32 v157, v154, v155
	global_store_dwordx2 v[160:161], v[156:157], off offset:512 nt
	global_store_dword v[158:159], v45, off offset:256
	v_pk_mul_f32 v[74:75], v[74:75], v[32:33] op_sel_hi:[1,0]
	v_pk_fma_f32 v[72:73], v[16:17], v[72:73], v[24:25]
	v_mov_b32_e32 v45, v33
	v_pk_fma_f32 v[66:67], v[22:23], v[64:65], v[30:31]
	v_pk_fma_f32 v[64:65], v[20:21], v[68:69], v[28:29]
	v_mov_b32_e32 v32, v33
	v_cvt_pk_fp8_f32 v45, v72, v73
	v_cvt_pk_fp8_f32 v32, v64, v65
	v_pk_fma_f32 v[74:75], v[18:19], v[74:75], v[26:27]
	ds_write_b128 v148, v[152:155] offset:1024
	v_cvt_pk_fp8_f32 v45, v74, v75 op_sel:[0,0,1]
	v_cvt_pk_fp8_f32 v32, v66, v67 op_sel:[0,0,1]
	v_cvt_pk_bf16_f32 v152, v72, v73
	v_cvt_pk_bf16_f32 v153, v74, v75
	global_store_dwordx2 v[160:161], v[152:153], off offset:1024 nt
	global_store_dword v[158:159], v45, off offset:512
	v_cvt_pk_bf16_f32 v68, v64, v65
	v_cvt_pk_bf16_f32 v69, v66, v67
	global_store_dwordx2 v[160:161], v[68:69], off offset:1536 nt
	global_store_dword v[158:159], v32, off offset:768
	v_lshlrev_b32_e32 v153, 16, v47
	v_lshlrev_b32_e32 v152, 16, v46
	v_and_b32_e32 v155, 0xffff0000, v47
	v_and_b32_e32 v154, 0xffff0000, v46
	v_lshlrev_b32_e32 v157, 16, v49
	v_lshlrev_b32_e32 v156, 16, v48
	v_and_b32_e32 v159, 0xffff0000, v49
	v_and_b32_e32 v158, 0xffff0000, v48
	ds_write_b128 v148, v[64:67] offset:3072
	v_pk_add_f32 v[64:65], v[152:153], v[154:155]
	v_pk_add_f32 v[66:67], v[156:157], v[158:159]
	ds_write_b128 v148, v[72:75] offset:2048
	v_add_f32_e32 v32, v64, v65
	v_pk_add_f32 v[66:67], v[66:67], v[66:67] op_sel_hi:[0,1]
	v_lshlrev_b32_e32 v72, 16, v50
	v_and_b32_e32 v73, 0xffff0000, v50
	v_lshlrev_b32_e32 v74, 16, v51
	v_and_b32_e32 v75, 0xffff0000, v51
	v_add_f32_e32 v65, 0, v32
	v_add_f32_e32 v69, v72, v73
	v_add_f32_e32 v71, v74, v75
	v_lshlrev_b32_e32 v68, 16, v54
	v_lshlrev_b32_e32 v66, 16, v55
	v_and_b32_e32 v64, 0xffff0000, v55
	v_pk_add_f32 v[160:161], v[68:69], v[70:71]
	v_pk_add_f32 v[162:163], v[66:67], v[64:65]
	v_mov_b32_e32 v45, v33
	v_pk_add_f32 v[160:161], v[160:161], v[162:163]
	s_nop 0
	v_add_f32_e32 v32, v160, v161
	s_nop 1
	v_add_f32_dpp v32, v32, v32 quad_perm:[1,0,3,2] row_mask:0xf bank_mask:0xf bound_ctrl:1
	s_nop 1
	v_add_f32_dpp v32, v32, v32 quad_perm:[2,3,0,1] row_mask:0xf bank_mask:0xf bound_ctrl:1
	s_nop 1
	v_add_f32_dpp v32, v32, v32 row_half_mirror row_mask:0xf bank_mask:0xf bound_ctrl:1
	s_nop 1
	v_add_f32_dpp v32, v32, v32 row_mirror row_mask:0xf bank_mask:0xf bound_ctrl:1
	s_nop 1
	v_mov_b32_dpp v45, v32 row_bcast:15 row_mask:0xa bank_mask:0xf
	v_add_f32_e32 v32, v32, v45
	v_mov_b32_e32 v45, v33
	s_nop 1
	v_mov_b32_dpp v45, v32 row_bcast:31 row_mask:0xc bank_mask:0xf
	v_add_f32_e32 v32, v32, v45
	v_mov_b32_e32 v45, v33
	v_readlane_b32 s0, v32, 63
	s_nop 1
	v_fmac_f32_e32 v154, s0, v210
	v_fmac_f32_e32 v155, s0, v210
	v_fmac_f32_e32 v153, s0, v210
	v_fmac_f32_e32 v152, s0, v210
	v_mov_b32_e32 v160, v153
	v_mov_b32_e32 v161, v155
	v_mov_b32_e32 v153, v154
	v_pk_mul_f32 v[162:163], v[160:161], v[160:161]
	v_pk_mul_f32 v[154:155], v[152:153], v[152:153]
	v_fmac_f32_e32 v158, s0, v210
	v_fmac_f32_e32 v159, s0, v210
	v_fmac_f32_e32 v157, s0, v210
	v_pk_mov_b32 v[172:173], v[154:155], v[162:163] op_sel:[1,0]
	v_mov_b32_e32 v155, v163
	v_fmac_f32_e32 v156, s0, v210
	v_mov_b32_e32 v162, v157
	v_mov_b32_e32 v163, v159
	v_mov_b32_e32 v157, v158
	v_pk_add_f32 v[154:155], v[172:173], v[154:155]
	v_pk_mul_f32 v[172:173], v[162:163], v[162:163]
	v_pk_mul_f32 v[158:159], v[156:157], v[156:157]
	v_fmac_f32_e32 v72, s0, v210
	v_pk_mov_b32 v[174:175], v[158:159], v[172:173] op_sel:[1,0]
	v_mov_b32_e32 v159, v173
	v_fmac_f32_e32 v73, s0, v210
	v_fmac_f32_e32 v74, s0, v210
	v_mul_f32_e32 v32, v72, v72
	v_pk_add_f32 v[158:159], v[174:175], v[158:159]
	v_fmac_f32_e32 v75, s0, v210
	v_pk_fma_f32 v[172:173], v[72:73], v[72:73], v[32:33] op_sel_hi:[1,1,0]
	v_mul_f32_e32 v32, v74, v74
	v_pk_add_f32 v[154:155], v[154:155], v[154:155] op_sel_hi:[0,1]
	v_pk_add_f32 v[158:159], v[158:159], v[158:159] op_sel_hi:[0,1]
	v_pk_fma_f32 v[174:175], v[74:75], v[74:75], v[32:33] op_sel_hi:[1,1,0]
	v_fmac_f32_e32 v64, s0, v210
	v_fmac_f32_e32 v66, s0, v210
	v_fmac_f32_e32 v70, s0, v210
	v_fmac_f32_e32 v68, s0, v210
	v_mul_f32_e32 v172, v68, v68
	v_mul_f32_e32 v174, v70, v70
	v_mul_f32_e32 v154, v66, v66
; #define LAS __attribute__((address_space(3)))
; __device__ __forceinline__ unsigned pk2(float lo, float hi) { unsigned r; asm("v_cvt_pk_bf16_f32 %0, %1, %2" : "=v"(r) : "v"(lo), "v"(hi)); return r; }
; __device__ __forceinline__ unsigned pk4_fp8(float a, float b, float c, float d) { int w = 0; w = __builtin_amdgcn_cvt_pk_fp8_f32(a, b, w, false); w = __builtin_amdgcn_cvt_pk_fp8_f32(c, d, w, true); return (unsigned)w; }
; __device__ __forceinline__ float bflo(unsigned u) { return __uint_as_float(u << 16); }
; __device__ __forceinline__ float bfhi(unsigned u) { return __uint_as_float(u & 0xffff0000u); }
; __device__ __forceinline__ void ln1_router_phase(const Args& a, int l, LAS unsigned char* lds, const int tid, const int rpt) {
;     ...
;         for (int rr = 0; rr < 2; ++rr) { const int lr = 2 * wave + rr;
;             f32x4 v[4]; float s = 0.f;
; #pragma unroll
;             for (int j = 0; j < 4; ++j) { const u32x2 w = pre[rr][j]; v[j] = (f32x4){bflo(w.x), bfhi(w.x), bflo(w.y), bfhi(w.y)}; s += (v[j][0] + v[j][1]) + (v[j][2] + v[j][3]); }
;             const float mean = wave_sum(s, lane) * (1.f / 1024.f); float s2 = 0.f;
; #pragma unroll
;             for (int j = 0; j < 4; ++j) { v[j] = v[j] - mean; s2 += (v[j][0] * v[j][0] + v[j][1] * v[j][1]) + (v[j][2] * v[j][2] + v[j][3] * v[j][3]); }
;             const float rstd = rsqrtf(wave_sum(s2, lane) * (1.f / 1024.f) + LN_EPS);
; #pragma unroll
;             for (int j = 0; j < 4; ++j) { const f32x4 y = v[j] * rstd * gv[j] + bv[j];
;                 u32x2 w; w.x = pk2(y[0], y[1]); w.y = pk2(y[2], y[3]); *(u32x2*)(x1b + (size_t)(tok0 + lr) * 1024 + 4 * (64 * j + lane)) = w;
;                 *(unsigned*)(x1q + (size_t)(tok0 + lr) * 1024 + 4 * (64 * j + lane)) = pk4_fp8(y[0], y[1], y[2], y[3]);
;                 *(LAS f32x4*)(X + lr * 1028 + 4 * (64 * j + lane)) = y; } }
;         __syncthreads();
;         { const int nt = tile + gridDim.x;
;           if (nt < NTOK / 16) {
; #pragma unroll
;             for (int rr = 0; rr < 2; ++rr)
; #pragma unroll
;                 for (int j = 0; j < 4; ++j) pre[rr][j] = *(const u32x2*)(ypre + (size_t)(nt * 16 + 2 * wave + rr) * 1024 + 4 * (64 * j + lane)); } }
	v_mul_f32_e32 v158, v64, v64
	v_pk_add_f32 v[172:173], v[172:173], v[174:175]
	v_pk_add_f32 v[154:155], v[154:155], v[158:159]
	v_mov_b32_e32 v69, v70
	v_pk_add_f32 v[154:155], v[172:173], v[154:155]
	v_mov_b32_e32 v67, v64
	v_add_f32_e32 v32, v154, v155
	s_nop 1
	v_add_f32_dpp v32, v32, v32 quad_perm:[1,0,3,2] row_mask:0xf bank_mask:0xf bound_ctrl:1
	s_nop 1
	v_add_f32_dpp v32, v32, v32 quad_perm:[2,3,0,1] row_mask:0xf bank_mask:0xf bound_ctrl:1
	s_nop 1
	v_add_f32_dpp v32, v32, v32 row_half_mirror row_mask:0xf bank_mask:0xf bound_ctrl:1
	s_nop 1
	v_add_f32_dpp v32, v32, v32 row_mirror row_mask:0xf bank_mask:0xf bound_ctrl:1
	s_nop 1
	v_mov_b32_dpp v45, v32 row_bcast:15 row_mask:0xa bank_mask:0xf
	v_add_f32_e32 v32, v32, v45
	v_mov_b32_e32 v45, v33
	s_nop 1
	v_mov_b32_dpp v45, v32 row_bcast:31 row_mask:0xc bank_mask:0xf
	v_add_f32_e32 v32, v32, v45
	s_nop 0
	v_readlane_b32 s0, v32, 63
	s_nop 1
	v_fma_f32 v32, s0, v247, v206
	v_cmp_gt_f32_e32 vcc, s33, v32
	v_mul_f32_e32 v45, 0x4b800000, v32
	s_add_i32 s0, s51, s27
	v_cndmask_b32_e32 v32, v32, v45, vcc
	v_rsq_f32_e32 v32, v32
	s_ashr_i32 s1, s0, 31
	s_lshl_b64 s[20:21], s[0:1], 10
	s_lshl_b64 s[0:1], s[0:1], 11
	v_mul_f32_e32 v45, 0x45800000, v32
	v_cndmask_b32_e32 v32, v32, v45, vcc
	v_pk_mul_f32 v[152:153], v[152:153], v[32:33] op_sel_hi:[1,0]
	v_mov_b32_e32 v45, v33
	v_pk_fma_f32 v[152:153], v[0:1], v[152:153], v[8:9]
	v_pk_mul_f32 v[154:155], v[160:161], v[32:33] op_sel_hi:[1,0]
	v_cvt_pk_fp8_f32 v45, v152, v153
	v_pk_fma_f32 v[154:155], v[2:3], v[154:155], v[10:11]
	v_cvt_pk_bf16_f32 v158, v152, v153
	v_lshl_add_u64 v[160:161], v[58:59], 0, s[0:1]
	v_cvt_pk_fp8_f32 v45, v154, v155 op_sel:[0,0,1]
	v_cvt_pk_bf16_f32 v159, v154, v155
	global_store_dwordx2 v[160:161], v[158:159], off nt
	v_lshl_add_u64 v[158:159], v[60:61], 0, s[20:21]
	ds_write_b128 v149, v[152:155]
	v_pk_mul_f32 v[152:153], v[156:157], v[32:33] op_sel_hi:[1,0]
	global_store_dword v[158:159], v45, off
	v_pk_fma_f32 v[152:153], v[4:5], v[152:153], v[12:13]
	v_mov_b32_e32 v45, v33
	v_cvt_pk_fp8_f32 v45, v152, v153
	v_pk_mul_f32 v[154:155], v[162:163], v[32:33] op_sel_hi:[1,0]
	v_pk_mul_f32 v[72:73], v[72:73], v[32:33] op_sel_hi:[1,0]
	v_pk_fma_f32 v[154:155], v[6:7], v[154:155], v[14:15]
	v_pk_mul_f32 v[68:69], v[68:69], v[32:33] op_sel_hi:[1,0]
	v_cvt_pk_fp8_f32 v45, v154, v155 op_sel:[0,0,1]
	v_pk_mul_f32 v[64:65], v[66:67], v[32:33] op_sel_hi:[1,0]
	v_cvt_pk_bf16_f32 v156, v152, v153
	v_cvt_pk_bf16_f32 v157, v154, v155
	global_store_dwordx2 v[160:161], v[156:157], off offset:512 nt
	global_store_dword v[158:159], v45, off offset:256
	v_pk_mul_f32 v[74:75], v[74:75], v[32:33] op_sel_hi:[1,0]
	v_pk_fma_f32 v[72:73], v[16:17], v[72:73], v[24:25]
	v_mov_b32_e32 v45, v33
	v_pk_fma_f32 v[66:67], v[22:23], v[64:65], v[30:31]
	v_pk_fma_f32 v[64:65], v[20:21], v[68:69], v[28:29]
	v_mov_b32_e32 v32, v33
	v_cvt_pk_fp8_f32 v45, v72, v73
	v_cvt_pk_fp8_f32 v32, v64, v65
	v_pk_fma_f32 v[74:75], v[18:19], v[74:75], v[26:27]
	v_readlane_b32 s0, v249, 49
	v_cvt_pk_fp8_f32 v45, v74, v75 op_sel:[0,0,1]
	v_cvt_pk_fp8_f32 v32, v66, v67 op_sel:[0,0,1]
	s_add_i32 s50, s50, s0
	s_cmpk_gt_i32 s50, 0x7ff
	s_cselect_b64 s[20:21], -1, 0
	s_and_b64 vcc, exec, s[20:21]
	ds_write_b128 v149, v[152:155] offset:1024
	v_cvt_pk_bf16_f32 v152, v72, v73
	v_cvt_pk_bf16_f32 v153, v74, v75
	global_store_dwordx2 v[160:161], v[152:153], off offset:1024 nt
	global_store_dword v[158:159], v45, off offset:512
	ds_write_b128 v149, v[72:75] offset:2048
	v_cvt_pk_bf16_f32 v68, v64, v65
	v_cvt_pk_bf16_f32 v69, v66, v67
	global_store_dwordx2 v[160:161], v[68:69], off offset:1536 nt
	global_store_dword v[158:159], v32, off offset:768
	ds_write_b128 v149, v[64:67] offset:3072
	s_waitcnt lgkmcnt(0)
	s_barrier
	s_cbranch_vccnz .LBB0_125
	s_lshl_b32 s0, s50, 4
	s_add_i32 s0, s0, s15
	s_ashr_i32 s1, s0, 31
	s_lshl_b64 s[22:23], s[0:1], 11
	s_or_b32 s0, s0, 1
	s_ashr_i32 s1, s0, 31
	s_lshl_b64 s[0:1], s[0:1], 11
	v_lshl_add_u64 v[42:43], v[62:63], 0, s[22:23]
	v_lshl_add_u64 v[54:55], v[62:63], 0, s[0:1]
	global_load_dwordx2 v[34:35], v[42:43], off nt
	global_load_dwordx2 v[36:37], v[42:43], off offset:512 nt
	global_load_dwordx2 v[40:41], v[42:43], off offset:1024 nt
	s_nop 0
	global_load_dwordx2 v[42:43], v[42:43], off offset:1536 nt
	s_nop 0
	global_load_dwordx2 v[46:47], v[54:55], off nt
	global_load_dwordx2 v[48:49], v[54:55], off offset:512 nt
	global_load_dwordx2 v[50:51], v[54:55], off offset:1024 nt
	s_nop 0
	global_load_dwordx2 v[54:55], v[54:55], off offset:1536 nt
